# code placement extended: 64-byte alignment on every MFMA-heavy loop head (GEMM mainloops, MEM/SB/FOX/MLA loops)
# speedup vs baseline: 1.0043x; 1.0003x over previous
; DI int tid8_op() { int t = threadIdx.x; asm volatile("" : "+v"(t)); return t; }
; #define PG8_STAGE(bufoff, gbase, voff) do { _Pragma("unroll") for (int _i = 0; _i < 2; ++_i) \
;         __builtin_amdgcn_global_load_lds((const unsigned*)((const char*)(gbase) + (voff)[_i]), (PG8_LAS unsigned*)(lds + (bufoff) + ldsw + _i * 8192), 16, 0, 0); } while (0)
; #define PG8_BAR __builtin_amdgcn_s_barrier()
; template <class Epi, class Sched, bool ALIGN_EPI = false, bool SP2 = false>
; __device__ __forceinline__ void gemm_phase(PG8_LAS unsigned char* lds, const Gemm g, const Sched& S, const Epi& E) {
;     const int tid = ::tid8_op(), wid = __builtin_amdgcn_readfirstlane(tid >> 6), lane = tid & 63, wr = wid >> 2, wc = wid & 3, fr = lane & 15, fq = lane >> 4;
;     const int K = g.K, nt = K / BK;
;     unsigned voffA[2], voffB[2];
; #pragma unroll
;     for (int i = 0; i < 2; ++i) { int R, C; stage_rc(tid * 16 + i * 8192, R, C); const int Rb = Epi::PERM ? ((R & ~31) + perm32(R & 31)) : R;
;         voffA[i] = (unsigned)(R * K + C) * 2u; voffB[i] = (unsigned)(Rb * K + C) * 2u; }
;     const size_t kstep = (size_t)(BK * 2);
;     const size_t hstep = (size_t)HALF * K * 2;
;     const size_t tstep = 2 * hstep;
;     const unsigned ldsw = (unsigned)wid * 1024u;
;     const int aoff = lds_byte(wr * 64 + fr, fq * 8), boff = lds_byte(wc * 32 + fr, fq * 8);
;     ...
;     Unit cur, nxt; int ui = 0;
;     if (!S.next(0, cur)) return;
;     f32x4 acc[2][2][4][2];
; #pragma unroll
;     for (int a = 0; a < 2; ++a)
; #pragma unroll
;         for (int b = 0; b < 2; ++b)
; #pragma unroll
;             for (int m = 0; m < 4; ++m)
; #pragma unroll
;                 for (int n = 0; n < 2; ++n) acc[a][b][m][n] = (f32x4){0.f, 0.f, 0.f, 0.f};
;     bf16x8 At[4][2], B0[2][2], B1[2][2];
;     const char* cA = (const char*)g.A + (size_t)cur.pm * tstep; const char* cB = (const char*)g.Bt + (size_t)cur.pn * tstep;
;     S.a_ready(cur);
;     if constexpr (SP2) {
;         PG8_STAGE(PG8_SB(0, 0), cB, voffB); PG8_STAGE(PG8_SB(0, 1), cB + hstep, voffB); PG8_STAGE(PG8_SA(0, 0), cA, voffA); PG8_STAGE(PG8_SA(0, 1), cA + hstep, voffA);
;         if (wr == 1) PG8_BAR;
;         PG8_WAIT_V(2); PG8_BAR;
;         PG8_STAGE(PG8_SB(1, 0), cB + kstep, voffB); PG8_STAGE(PG8_SA(1, 0), cA + kstep, voffA); PG8_STAGE(PG8_SB(1, 1), cB + hstep + kstep, voffB);
;         PG8_WAIT_V(6); PG8_BAR;
.LBB0_406:
	v_mov_b32_e32 v135, v1
	v_lshl_add_u64 v[8:9], s[6:7], 0, v[134:135]
	v_mov_b32_e32 v131, v1
	s_add_i32 s52, s3, 0x18000
	v_lshl_add_u64 v[10:11], s[6:7], 0, v[130:131]
	v_mov_b32_e32 v137, v1
	s_and_b32 s13, s4, 3
	v_lshl_add_u64 v[8:9], v[8:9], 0, s[50:51]
	s_mov_b32 m0, s52
	s_add_i32 s53, s3, 0x1a000
	v_lshl_add_u64 v[12:13], s[22:23], 0, v[136:137]
	v_mov_b32_e32 v133, v1
	s_lshl_b32 s16, s12, 13
	s_lshl_b32 s47, s13, 5
	s_lshl_b32 s13, s13, 12
	s_waitcnt vmcnt(2)
	s_barrier
	global_load_lds_dwordx4 v[8:9], off
	v_lshl_add_u64 v[8:9], v[10:11], 0, s[50:51]
	s_mov_b32 m0, s53
	s_add_i32 s54, s3, 0x8000
	s_add_i32 s55, s3, 0xa000
	v_lshl_add_u64 v[14:15], s[22:23], 0, v[132:133]
	global_load_lds_dwordx4 v[8:9], off
	v_lshl_add_u64 v[8:9], v[12:13], 0, s[50:51]
	s_mov_b32 m0, s54
	s_add_u32 s14, s6, 0x40080
	global_load_lds_dwordx4 v[8:9], off
	v_lshl_add_u64 v[8:9], v[14:15], 0, s[50:51]
	s_mov_b32 m0, s55
	s_addc_u32 s15, s7, 0
	s_add_i32 s56, s3, 0x1c000
	global_load_lds_dwordx4 v[8:9], off
	v_lshl_add_u64 v[8:9], s[14:15], 0, v[134:135]
	s_mov_b32 m0, s56
	s_add_i32 s57, s3, 0x1e000
	global_load_lds_dwordx4 v[8:9], off
	v_lshl_add_u64 v[8:9], s[14:15], 0, v[130:131]
	s_mov_b32 m0, s57
	s_cmpk_lt_u32 s5, 0x100
	global_load_lds_dwordx4 v[8:9], off
	v_lshrrev_b32_e32 v9, 1, v2
	v_and_b32_e32 v138, 24, v9
	v_and_b32_e32 v8, 15, v2
	v_lshlrev_b32_e32 v9, 1, v138
	v_lshlrev_b32_e32 v2, 2, v2
	v_lshl_or_b32 v139, s12, 6, v8
	v_lshl_or_b32 v8, v8, 6, v9
	v_and_b32_e32 v2, 32, v2
	v_bitop3_b32 v141, v8, s16, v2 bitop3:0xde
	v_bitop3_b32 v2, v8, s13, v2 bitop3:0xde
	v_lshlrev_b32_e32 v8, 14, v0
	v_and_b32_e32 v8, 0xffff8000, v8
	v_lshl_add_u32 v3, v3, 11, v8
	v_and_b32_e32 v0, 1, v0
	v_lshl_or_b32 v0, v0, 6, v3
	v_lshl_add_u32 v144, v4, 1, v0
	v_lshlrev_b32_e32 v0, 14, v6
	v_and_b32_e32 v0, 0xffff8000, v0
	s_waitcnt vmcnt(6)
	v_lshl_add_u32 v0, v5, 11, v0
	v_and_b32_e32 v3, 1, v6
	s_cselect_b64 s[12:13], -1, 0
	v_and_or_b32 v140, s47, 32, v138
	s_add_u32 s58, s8, 0x7880000
	v_lshl_or_b32 v0, v3, 6, v0
	v_readlane_b32 s0, v253, 44
	v_lshlrev_b32_e32 v142, 13, v140
	s_addc_u32 s59, s9, 0
	s_bfe_u32 s60, s4, 0x10001
	v_mov_b32_e32 v145, v1
	v_lshl_add_u32 v146, v7, 1, v0
	v_mov_b32_e32 v147, v1
	s_mov_b32 s61, 0
	v_or_b32_e32 v143, 0x10000, v2
	v_add_u32_e32 v152, 0x10400, v2
	v_add_u32_e32 v153, 0x10800, v2
	v_add_u32_e32 v154, 0x10c00, v2
	v_or_b32_e32 v155, 0x14000, v2
	v_add_u32_e32 v156, 0x14400, v2
	v_add_u32_e32 v157, 0x14800, v2
	v_add_u32_e32 v158, 0x14c00, v2
	s_add_i32 s62, s3, 0xc000
	s_add_i32 s66, s3, 0xe000
	v_or_b32_e32 v159, 0x18000, v2
	v_add_u32_e32 v160, 0x18400, v2
	v_add_u32_e32 v161, 0x18800, v2
	v_add_u32_e32 v162, 0x18c00, v2
	v_or_b32_e32 v163, 0x1c000, v2
	v_add_u32_e32 v164, 0x1c400, v2
	v_add_u32_e32 v165, 0x1c800, v2
	v_add_u32_e32 v166, 0x1cc00, v2
	v_readlane_b32 s26, v253, 38
	s_mov_b32 s27, s0
	s_barrier
	v_readlane_b32 s1, v253, 45
	s_branch .LBB0_409
	.p2align	6
.LBB0_407:
	s_mov_b64 s[4:5], 0
	.p2align	6

;     __device__ __forceinline__ bool next(int i, pg8::Unit& o) const { if (i != 0) return false; o = u; return true; }
; template <class Epi, class Sched, bool ALIGN_EPI = false, bool SP2 = false>
; __device__ __forceinline__ void gemm_phase(PG8_LAS unsigned char* lds, const Gemm g, const Sched& S, const Epi& E) {
;     ...
;     for (;;) {
;         const bool has_next = S.next(ui + 1, nxt);
;         const char* nA = has_next ? (const char*)g.A + (size_t)nxt.pm * tstep : cA; const char* nB = has_next ? (const char*)g.Bt + (size_t)nxt.pn * tstep : cB;
;         for (int t = 0; t < nt; t += 2) {
;             const bool last = (t == nt - 2);
;             const char* a1 = cA + (size_t)(t + 1) * kstep;
;             const char* a2 = last ? nA : cA + (size_t)(t + 2) * kstep; const char* b2 = last ? nB : cB + (size_t)(t + 2) * kstep;
;     ...
;         for (int a = 0; a < 2; ++a)
; #pragma unroll
;             for (int b = 0; b < 2; ++b)
; #pragma unroll
;                 for (int m = 0; m < 4; ++m)
; #pragma unroll
;                     for (int n = 0; n < 2; ++n) acc[a][b][m][n] = (f32x4){0.f, 0.f, 0.f, 0.f};
;         cur = nxt; cA = nA; cB = nB; ++ui;
.LBB0_411:
	s_ashr_i32 s17, s16, 31
	s_lshl_b64 s[18:19], s[16:17], 19
	s_add_u32 s18, s34, s18
	s_addc_u32 s19, s35, s19
	s_and_b64 s[20:21], s[4:5], exec
	s_cselect_b32 s17, s19, s23
	s_cselect_b32 s28, s18, s22
	s_ashr_i32 s15, s14, 31
	s_lshl_b64 s[20:21], s[14:15], 19
	s_add_u32 s20, s36, s20
	s_addc_u32 s21, s37, s21
	s_and_b64 s[24:25], s[4:5], exec
	s_cselect_b32 s15, s21, s7
	s_cselect_b32 s29, s20, s6
	s_add_u32 s30, s6, 0x100
	s_addc_u32 s31, s7, 0
	s_add_u32 s6, s22, 0x40080
	v_mov_b32_e32 v2, 0
	s_addc_u32 s7, s23, 0
	s_mov_b32 s48, -2
	v_mov_b32_e32 v3, v2
	v_mov_b32_e32 v4, v2
	v_mov_b32_e32 v5, v2
	v_mov_b32_e32 v6, v2
	v_mov_b32_e32 v7, v2
	v_mov_b32_e32 v8, v2
	v_mov_b32_e32 v9, v2
	v_mov_b32_e32 v10, v2
	v_mov_b32_e32 v11, v2
	v_mov_b32_e32 v12, v2
	v_mov_b32_e32 v13, v2
	v_mov_b32_e32 v14, v2
	v_mov_b32_e32 v15, v2
	v_mov_b32_e32 v16, v2
	v_mov_b32_e32 v17, v2
	v_mov_b32_e32 v18, v2
	v_mov_b32_e32 v19, v2
	v_mov_b32_e32 v20, v2
	v_mov_b32_e32 v21, v2
	v_mov_b32_e32 v22, v2
	v_mov_b32_e32 v23, v2
	v_mov_b32_e32 v24, v2
	v_mov_b32_e32 v25, v2
	v_mov_b32_e32 v26, v2
	v_mov_b32_e32 v27, v2
	v_mov_b32_e32 v28, v2
	v_mov_b32_e32 v29, v2
	v_mov_b32_e32 v30, v2
	v_mov_b32_e32 v31, v2
	v_mov_b32_e32 v32, v2
	v_mov_b32_e32 v33, v2
	v_mov_b32_e32 v66, v2
	v_mov_b32_e32 v67, v2
	v_mov_b32_e32 v68, v2
	v_mov_b32_e32 v69, v2
	v_mov_b32_e32 v70, v2
	v_mov_b32_e32 v71, v2
	v_mov_b32_e32 v72, v2
	v_mov_b32_e32 v73, v2
	v_mov_b32_e32 v74, v2
	v_mov_b32_e32 v75, v2
	v_mov_b32_e32 v76, v2
	v_mov_b32_e32 v77, v2
	v_mov_b32_e32 v78, v2
	v_mov_b32_e32 v79, v2
	v_mov_b32_e32 v80, v2
	v_mov_b32_e32 v81, v2
	v_mov_b32_e32 v82, v2
	v_mov_b32_e32 v83, v2
	v_mov_b32_e32 v84, v2
	v_mov_b32_e32 v85, v2
	v_mov_b32_e32 v86, v2
	v_mov_b32_e32 v87, v2
	v_mov_b32_e32 v88, v2
	v_mov_b32_e32 v89, v2
	v_mov_b32_e32 v90, v2
	v_mov_b32_e32 v91, v2
	v_mov_b32_e32 v92, v2
	v_mov_b32_e32 v93, v2
	v_mov_b32_e32 v94, v2
	v_mov_b32_e32 v95, v2
	v_mov_b32_e32 v96, v2
	v_mov_b32_e32 v97, v2
	v_mov_b32_e32 v34, v2
	v_mov_b32_e32 v35, v2
	v_mov_b32_e32 v36, v2
	v_mov_b32_e32 v37, v2
	v_mov_b32_e32 v38, v2
	v_mov_b32_e32 v39, v2
	v_mov_b32_e32 v40, v2
	v_mov_b32_e32 v41, v2
	v_mov_b32_e32 v42, v2
	v_mov_b32_e32 v43, v2
	v_mov_b32_e32 v44, v2
	v_mov_b32_e32 v45, v2
	v_mov_b32_e32 v46, v2
	v_mov_b32_e32 v47, v2
	v_mov_b32_e32 v48, v2
	v_mov_b32_e32 v49, v2
	v_mov_b32_e32 v50, v2
	v_mov_b32_e32 v51, v2
	v_mov_b32_e32 v52, v2
	v_mov_b32_e32 v53, v2
	v_mov_b32_e32 v54, v2
	v_mov_b32_e32 v55, v2
	v_mov_b32_e32 v56, v2
	v_mov_b32_e32 v57, v2
	v_mov_b32_e32 v58, v2
	v_mov_b32_e32 v59, v2
	v_mov_b32_e32 v60, v2
	v_mov_b32_e32 v61, v2
	v_mov_b32_e32 v62, v2
	v_mov_b32_e32 v63, v2
	v_mov_b32_e32 v64, v2
	v_mov_b32_e32 v65, v2
	v_mov_b32_e32 v98, v2
	v_mov_b32_e32 v99, v2
	v_mov_b32_e32 v100, v2
	v_mov_b32_e32 v101, v2
	v_mov_b32_e32 v102, v2
	v_mov_b32_e32 v103, v2
	v_mov_b32_e32 v104, v2
	v_mov_b32_e32 v105, v2
	v_mov_b32_e32 v106, v2
	v_mov_b32_e32 v107, v2
	v_mov_b32_e32 v108, v2
	v_mov_b32_e32 v109, v2
	v_mov_b32_e32 v110, v2
	v_mov_b32_e32 v111, v2
	v_mov_b32_e32 v112, v2
	v_mov_b32_e32 v113, v2
	v_mov_b32_e32 v114, v2
	v_mov_b32_e32 v115, v2
	v_mov_b32_e32 v116, v2
	v_mov_b32_e32 v117, v2
	v_mov_b32_e32 v118, v2
	v_mov_b32_e32 v119, v2
	v_mov_b32_e32 v120, v2
	v_mov_b32_e32 v121, v2
	v_mov_b32_e32 v122, v2
	v_mov_b32_e32 v123, v2
	v_mov_b32_e32 v124, v2
	v_mov_b32_e32 v125, v2
	v_mov_b32_e32 v126, v2
	v_mov_b32_e32 v127, v2
	v_mov_b32_e32 v128, v2
	v_mov_b32_e32 v129, v2
	.p2align	6

; DI int tid_op() { int t = threadIdx.x & 255; asm volatile("" : "+v"(t)); return t; }
; DI int vhalf() { return __builtin_amdgcn_readfirstlane((int)(threadIdx.x >> 8)); }
; #define VB ((int)blockIdx.x * 2 + vhalf())
; DI void phase1(const Params& p, int l, unsigned char* smem) {
;     ...
;         unsigned char* hs = smem + vhalf() * HALF_SMEM;
;         const int t4 = tid_op(), lane4 = t4 & 63, w4 = t4 >> 6, wr4 = w4 >> 1, wc4 = w4 & 1, r4 = lane4 & 31, h4 = lane4 >> 5;
;         for (int t = VB; t < 256; t += VG) {
;             const int m0 = t * 128;
;             f32x16 acc[2];
; #pragma unroll
;             for (int i = 0; i < 16; ++i) { acc[0][i] = 0.f; acc[1][i] = 0.f; }
;             gemm_accum_n1(acc, XB + (size_t)m0 * 1024, 1024, W + (size_t)3584 * 1024, 1024, 16, hs);
;             const int row0 = m0 + 64 * wr4, b = row0 >> 13, s0 = row0 & (S_ - 1);
.LBB0_497:
	v_readfirstlane_b32 s3, v214
	s_lshr_b32 s16, s3, 8
	v_mov_b32_e32 v0, v215
	s_add_i32 s24, s16, s74
	v_ashrrev_i32_e32 v2, 7, v0
	v_bfe_u32 v59, v0, 5, 1
	s_mul_i32 s3, s16, 0x12400
	v_bfe_u32 v61, v0, 6, 1
	v_and_b32_e32 v58, 31, v0
	s_cmpk_gt_i32 s24, 0xff
	v_lshlrev_b32_e32 v122, 6, v2
	v_lshlrev_b32_e32 v60, 2, v59
	s_cbranch_scc1 .LBB0_512
	s_add_u32 s10, s36, 0x700000
	s_addc_u32 s11, s37, 0
	s_mov_b32 s0, s91
	v_readlane_b32 s80, v253, 0
	s_add_u32 s12, s8, 0x15c80000
	v_lshlrev_b32_e32 v2, 2, v58
	v_mov_b32_e32 v3, v1
	v_readlane_b32 s91, v253, 11
	s_addc_u32 s13, s9, 0
	v_lshl_add_u64 v[2:3], s[8:9], 0, v[2:3]
	s_mov_b64 s[14:15], 0x15880000
	s_mov_b32 s91, s0
	v_readlane_b32 s0, v254, 44
	v_lshl_add_u64 v[62:63], v[2:3], 0, s[14:15]
	v_readlane_b32 s1, v254, 45
	s_add_u32 s14, s8, s0
	s_addc_u32 s15, s9, s1
	s_add_u32 s25, s8, 0x3880080
	v_lshl_add_u32 v0, s72, 2, v58
	v_readlane_b32 s81, v253, 1
	v_readlane_b32 s82, v253, 2
	v_readlane_b32 s83, v253, 3
	v_readlane_b32 s84, v253, 4
	v_readlane_b32 s85, v253, 5
	v_readlane_b32 s86, v253, 6
	v_readlane_b32 s87, v253, 7
	v_readlane_b32 s88, v253, 8
	v_readlane_b32 s89, v253, 9
	v_readlane_b32 s90, v253, 10
	v_readlane_b32 s92, v253, 12
	v_readlane_b32 s93, v253, 13
	v_readlane_b32 s94, v253, 14
	v_readlane_b32 s95, v253, 15
	s_addc_u32 s26, s9, 0
	s_lshl_b32 s16, s16, 7
	v_readlane_b32 s0, v254, 20
	v_cmp_ne_u32_e64 s[4:5], 0, v61
	v_cmp_gt_u32_e64 s[6:7], 4, v58
	s_mov_b32 s95, 0x7fffffe0
	s_mov_b32 s94, 0x800000
	s_mov_b32 s93, 0xfffffc0
	s_movk_i32 s92, 0x90
	s_movk_i32 s90, 0x1000
	s_mov_b32 s89, 0xc000
	s_mov_b32 s88, 0x1c000
	s_mov_b32 s87, 0x18000
	s_movk_i32 s86, 0x4000
	s_mov_b32 s85, 0x14000
	s_movk_i32 s79, 0xc0
	v_readlane_b32 s84, v254, 51
	v_readlane_b32 s83, v254, 50
	s_movk_i32 s82, 0xe1
	v_lshl_add_u64 v[64:65], v[0:1], 2, s[80:81]
	s_add_i32 s16, s0, s16
	s_branch .LBB0_500
	.p2align	6

; #define PG8_STAGE(bufoff, gbase, voff) do { _Pragma("unroll") for (int _i = 0; _i < 2; ++_i) \
;         __builtin_amdgcn_global_load_lds((const unsigned*)((const char*)(gbase) + (voff)[_i]), (PG8_LAS unsigned*)(lds + (bufoff) + ldsw + _i * 8192), 16, 0, 0); } while (0)
; #define PG8_WAIT_V(n) asm volatile("s_waitcnt vmcnt(" #n ")" ::: "memory")
; #define PG8_BAR __builtin_amdgcn_s_barrier()
; template <class Epi, class Sched, bool ALIGN_EPI = false, bool SP2 = false>
; __device__ __forceinline__ void gemm_phase(PG8_LAS unsigned char* lds, const Gemm g, const Sched& S, const Epi& E) {
;     ...
;     f32x4 acc[2][2][4][2];
; #pragma unroll
;     for (int a = 0; a < 2; ++a)
; #pragma unroll
;         for (int b = 0; b < 2; ++b)
; #pragma unroll
;             for (int m = 0; m < 4; ++m)
; #pragma unroll
;                 for (int n = 0; n < 2; ++n) acc[a][b][m][n] = (f32x4){0.f, 0.f, 0.f, 0.f};
;     bf16x8 At[4][2], B0[2][2], B1[2][2];
;     const char* cA = (const char*)g.A + (size_t)cur.pm * tstep; const char* cB = (const char*)g.Bt + (size_t)cur.pn * tstep;
;     S.a_ready(cur);
;     if constexpr (SP2) {
;         PG8_STAGE(PG8_SB(0, 0), cB, voffB); PG8_STAGE(PG8_SB(0, 1), cB + hstep, voffB); PG8_STAGE(PG8_SA(0, 0), cA, voffA); PG8_STAGE(PG8_SA(0, 1), cA + hstep, voffA);
;         if (wr == 1) PG8_BAR;
;         PG8_WAIT_V(2); PG8_BAR;
;         PG8_STAGE(PG8_SB(1, 0), cB + kstep, voffB); PG8_STAGE(PG8_SA(1, 0), cA + kstep, voffA); PG8_STAGE(PG8_SB(1, 1), cB + hstep + kstep, voffB);
;         PG8_WAIT_V(6); PG8_BAR;
;     } else {
;         PG8_STAGE(PG8_SB(0, 0), cB, voffB); PG8_STAGE(PG8_SA(0, 0), cA, voffA); PG8_STAGE(PG8_SB(0, 1), cB + hstep, voffB); PG8_STAGE(PG8_SA(0, 1), cA + hstep, voffA);
;         if (wr == 1) PG8_BAR;
;         PG8_WAIT_V(4); PG8_BAR;
;         PG8_STAGE(PG8_SB(1, 0), cB + kstep, voffB); PG8_STAGE(PG8_SA(1, 0), cA + kstep, voffA); PG8_STAGE(PG8_SB(1, 1), cB + hstep + kstep, voffB);
;         PG8_WAIT_V(6); PG8_BAR;
.LBB0_589:
	v_lshl_add_u64 v[4:5], s[4:5], 0, v[0:1]
	v_mov_b32_e32 v135, v1
	s_add_i32 s56, s41, 0x18000
	v_lshl_add_u64 v[6:7], s[4:5], 0, v[134:135]
	v_mov_b32_e32 v131, v1
	v_bfe_u32 v140, v2, 4, 2
	v_and_b32_e32 v141, 15, v2
	v_lshl_add_u64 v[2:3], v[4:5], 0, s[50:51]
	s_mov_b32 m0, s56
	s_add_i32 s57, s41, 0x1a000
	v_lshl_add_u64 v[12:13], s[18:19], 0, v[130:131]
	v_mov_b32_e32 v133, v1
	s_waitcnt vmcnt(2)
	s_barrier
	global_load_lds_dwordx4 v[2:3], off
	v_lshl_add_u64 v[2:3], v[6:7], 0, s[50:51]
	s_mov_b32 m0, s57
	s_add_i32 s58, s41, 0x8000
	v_lshl_add_u64 v[14:15], s[18:19], 0, v[132:133]
	global_load_lds_dwordx4 v[2:3], off
	v_lshl_add_u64 v[2:3], v[12:13], 0, s[50:51]
	s_mov_b32 m0, s58
	s_add_i32 s59, s41, 0xa000
	v_lshl_add_u64 v[8:9], s[22:23], 0, v[0:1]
	global_load_lds_dwordx4 v[2:3], off
	v_lshl_add_u64 v[2:3], v[14:15], 0, s[50:51]
	s_mov_b32 m0, s59
	s_add_i32 s60, s41, 0x1c000
	v_lshl_add_u64 v[10:11], s[22:23], 0, v[134:135]
	global_load_lds_dwordx4 v[2:3], off
	v_lshl_add_u64 v[2:3], v[8:9], 0, s[50:51]
	s_mov_b32 m0, s60
	s_add_i32 s61, s41, 0x1e000
	global_load_lds_dwordx4 v[2:3], off
	v_lshl_add_u64 v[2:3], v[10:11], 0, s[50:51]
	s_mov_b32 m0, s61
	s_lshl_b32 s3, s3, 5
	global_load_lds_dwordx4 v[2:3], off
	s_waitcnt vmcnt(6)
	s_lshl_b32 s40, s69, 6
	s_and_b32 s3, s3, 0x60
	v_mov_b32_e32 v129, 0
	s_cmp_lt_i32 s20, 64
	v_mov_b32_e32 v128, v129
	v_mov_b32_e32 v127, v129
	v_mov_b32_e32 v126, v129
	v_mov_b32_e32 v125, v129
	v_mov_b32_e32 v124, v129
	v_mov_b32_e32 v123, v129
	v_mov_b32_e32 v122, v129
	v_mov_b32_e32 v121, v129
	v_mov_b32_e32 v120, v129
	v_mov_b32_e32 v119, v129
	v_mov_b32_e32 v118, v129
	v_mov_b32_e32 v117, v129
	v_mov_b32_e32 v116, v129
	v_mov_b32_e32 v115, v129
	v_mov_b32_e32 v114, v129
	v_mov_b32_e32 v113, v129
	v_mov_b32_e32 v112, v129
	v_mov_b32_e32 v111, v129
	v_mov_b32_e32 v110, v129
	v_mov_b32_e32 v109, v129
	v_mov_b32_e32 v108, v129
	v_mov_b32_e32 v107, v129
	v_mov_b32_e32 v106, v129
	v_mov_b32_e32 v105, v129
	v_mov_b32_e32 v104, v129
	v_mov_b32_e32 v103, v129
	v_mov_b32_e32 v102, v129
	v_mov_b32_e32 v101, v129
	v_mov_b32_e32 v100, v129
	v_mov_b32_e32 v99, v129
	v_mov_b32_e32 v98, v129
	v_mov_b32_e32 v65, v129
	v_mov_b32_e32 v64, v129
	v_mov_b32_e32 v63, v129
	v_mov_b32_e32 v62, v129
	v_mov_b32_e32 v61, v129
	v_mov_b32_e32 v60, v129
	v_mov_b32_e32 v59, v129
	v_mov_b32_e32 v58, v129
	v_mov_b32_e32 v57, v129
	v_mov_b32_e32 v56, v129
	v_mov_b32_e32 v55, v129
	v_mov_b32_e32 v54, v129
	v_mov_b32_e32 v53, v129
	v_mov_b32_e32 v52, v129
	v_mov_b32_e32 v51, v129
	v_mov_b32_e32 v50, v129
	v_mov_b32_e32 v49, v129
	v_mov_b32_e32 v48, v129
	v_mov_b32_e32 v47, v129
	v_mov_b32_e32 v46, v129
	v_mov_b32_e32 v45, v129
	v_mov_b32_e32 v44, v129
	v_mov_b32_e32 v43, v129
	v_mov_b32_e32 v42, v129
	v_mov_b32_e32 v41, v129
	v_mov_b32_e32 v40, v129
	v_mov_b32_e32 v39, v129
	v_mov_b32_e32 v38, v129
	v_mov_b32_e32 v37, v129
	v_mov_b32_e32 v36, v129
	v_mov_b32_e32 v35, v129
	v_mov_b32_e32 v34, v129
	v_mov_b32_e32 v97, v129
	v_mov_b32_e32 v96, v129
	v_mov_b32_e32 v95, v129
	v_mov_b32_e32 v94, v129
	v_mov_b32_e32 v93, v129
	v_mov_b32_e32 v92, v129
	v_mov_b32_e32 v91, v129
	v_mov_b32_e32 v90, v129
	v_mov_b32_e32 v89, v129
	v_mov_b32_e32 v88, v129
	v_mov_b32_e32 v87, v129
	v_mov_b32_e32 v86, v129
	v_mov_b32_e32 v85, v129
	v_mov_b32_e32 v84, v129
	v_mov_b32_e32 v83, v129
	v_mov_b32_e32 v82, v129
	v_mov_b32_e32 v81, v129
	v_mov_b32_e32 v80, v129
	v_mov_b32_e32 v79, v129
	v_mov_b32_e32 v78, v129
	v_mov_b32_e32 v77, v129
	v_mov_b32_e32 v76, v129
	v_mov_b32_e32 v75, v129
	v_mov_b32_e32 v74, v129
	v_mov_b32_e32 v73, v129
	v_mov_b32_e32 v72, v129
	v_mov_b32_e32 v71, v129
	v_mov_b32_e32 v70, v129
	v_mov_b32_e32 v69, v129
	v_mov_b32_e32 v68, v129
	v_mov_b32_e32 v67, v129
	v_mov_b32_e32 v66, v129
	v_mov_b32_e32 v33, v129
	v_mov_b32_e32 v32, v129
	v_mov_b32_e32 v31, v129
	v_mov_b32_e32 v30, v129
	v_mov_b32_e32 v29, v129
	v_mov_b32_e32 v28, v129
	v_mov_b32_e32 v27, v129
	v_mov_b32_e32 v26, v129
	v_mov_b32_e32 v25, v129
	v_mov_b32_e32 v24, v129
	v_mov_b32_e32 v23, v129
	v_mov_b32_e32 v22, v129
	v_mov_b32_e32 v21, v129
	v_mov_b32_e32 v20, v129
	v_mov_b32_e32 v19, v129
	v_mov_b32_e32 v18, v129
	v_mov_b32_e32 v17, v129
	v_mov_b32_e32 v16, v129
	v_mov_b32_e32 v15, v129
	v_mov_b32_e32 v14, v129
	v_mov_b32_e32 v13, v129
	v_mov_b32_e32 v12, v129
	v_mov_b32_e32 v11, v129
	v_mov_b32_e32 v10, v129
	v_mov_b32_e32 v9, v129
	v_mov_b32_e32 v8, v129
	v_mov_b32_e32 v7, v129
	v_mov_b32_e32 v6, v129
	v_mov_b32_e32 v5, v129
	v_mov_b32_e32 v4, v129
	v_mov_b32_e32 v3, v129
	v_mov_b32_e32 v2, v129
	s_barrier
; DI int tid8_op() { int t = threadIdx.x; asm volatile("" : "+v"(t)); return t; }
; template <class Epi, class Sched, bool ALIGN_EPI = false, bool SP2 = false>
; __device__ __forceinline__ void gemm_phase(PG8_LAS unsigned char* lds, const Gemm g, const Sched& S, const Epi& E) {
;     const int tid = ::tid8_op(), wid = __builtin_amdgcn_readfirstlane(tid >> 6), lane = tid & 63, wr = wid >> 2, wc = wid & 3, fr = lane & 15, fq = lane >> 4;
;     const int K = g.K, nt = K / BK;
;     unsigned voffA[2], voffB[2];
; #pragma unroll
;     for (int i = 0; i < 2; ++i) { int R, C; stage_rc(tid * 16 + i * 8192, R, C); const int Rb = Epi::PERM ? ((R & ~31) + perm32(R & 31)) : R;
;         voffA[i] = (unsigned)(R * K + C) * 2u; voffB[i] = (unsigned)(Rb * K + C) * 2u; }
;     const size_t kstep = (size_t)(BK * 2);
;     const size_t hstep = (size_t)HALF * K * 2;
;     const size_t tstep = 2 * hstep;
;     const unsigned ldsw = (unsigned)wid * 1024u;
;     const int aoff = lds_byte(wr * 64 + fr, fq * 8), boff = lds_byte(wc * 32 + fr, fq * 8);
;     ...
;     f32x4 acc[2][2][4][2];
; #pragma unroll
;     for (int a = 0; a < 2; ++a)
; #pragma unroll
;         for (int b = 0; b < 2; ++b)
; #pragma unroll
;             for (int m = 0; m < 4; ++m)
; #pragma unroll
;                 for (int n = 0; n < 2; ++n) acc[a][b][m][n] = (f32x4){0.f, 0.f, 0.f, 0.f};
;     bf16x8 At[4][2], B0[2][2], B1[2][2];
;     const char* cA = (const char*)g.A + (size_t)cur.pm * tstep; const char* cB = (const char*)g.Bt + (size_t)cur.pn * tstep;
	s_cbranch_scc1 .LBB0_592
	s_lshr_b32 s22, s21, 26
	s_add_i32 s22, s20, s22
	v_or_b32_e32 v2, s40, v141
	s_ashr_i32 s62, s22, 6
	v_lshlrev_b32_e32 v3, 4, v140
	v_lshlrev_b32_e32 v4, 6, v2
	s_movk_i32 s22, 0x3c0
	v_lshlrev_b32_e32 v2, 2, v2
	v_lshlrev_b32_e32 v5, 2, v141
	v_and_or_b32 v4, v4, s22, v3
	v_and_b32_e32 v2, 32, v2
	v_lshl_or_b32 v3, v141, 6, v3
	v_and_b32_e32 v5, 32, v5
	s_lshl_b32 s22, s69, 13
	s_lshl_b32 s23, s3, 7
	v_bitop3_b32 v142, v4, s22, v2 bitop3:0xde
	v_bitop3_b32 v143, v3, s23, v5 bitop3:0xde
	s_lshl_b64 s[22:23], s[16:17], 9
	s_bitset1_b32 s22, 8
	s_mul_i32 s21, s22, s21
	s_mul_hi_u32 s69, s22, s20
	s_add_i32 s21, s69, s21
	s_mul_i32 s23, s23, s20
	s_add_i32 s66, s62, -2
	s_add_i32 s21, s21, s23
	s_mul_i32 s22, s22, s20
	v_add_u32_e32 v2, v145, v136
	s_add_u32 s20, s8, s22
	v_add_lshl_u32 v2, v2, v137, 1
	v_mov_b32_e32 v3, v1
	s_addc_u32 s21, s9, s21
	v_lshl_add_u64 v[136:137], s[20:21], 0, v[2:3]
	v_add_u32_e32 v2, v144, v138
	v_add_lshl_u32 v2, v2, v139, 1
	v_lshl_add_u64 v[138:139], s[20:21], 0, v[2:3]
	v_mov_b32_e32 v2, 0
	s_mov_b32 s22, 0
	s_mov_b64 s[20:21], 0x7880080
	v_mov_b32_e32 v3, v2
	v_mov_b32_e32 v4, v2
	v_mov_b32_e32 v5, v2
	v_mov_b32_e32 v6, v2
	v_mov_b32_e32 v7, v2
	v_mov_b32_e32 v8, v2
	v_mov_b32_e32 v9, v2
	v_mov_b32_e32 v10, v2
	v_mov_b32_e32 v11, v2
	v_mov_b32_e32 v12, v2
	v_mov_b32_e32 v13, v2
	v_mov_b32_e32 v14, v2
	v_mov_b32_e32 v15, v2
	v_mov_b32_e32 v16, v2
	v_mov_b32_e32 v17, v2
	v_mov_b32_e32 v18, v2
	v_mov_b32_e32 v19, v2
	v_mov_b32_e32 v20, v2
	v_mov_b32_e32 v21, v2
	v_mov_b32_e32 v22, v2
	v_mov_b32_e32 v23, v2
	v_mov_b32_e32 v24, v2
	v_mov_b32_e32 v25, v2
	v_mov_b32_e32 v26, v2
	v_mov_b32_e32 v27, v2
	v_mov_b32_e32 v28, v2
	v_mov_b32_e32 v29, v2
	v_mov_b32_e32 v30, v2
	v_mov_b32_e32 v31, v2
	v_mov_b32_e32 v32, v2
	v_mov_b32_e32 v33, v2
	v_mov_b32_e32 v66, v2
	v_mov_b32_e32 v67, v2
	v_mov_b32_e32 v68, v2
	v_mov_b32_e32 v69, v2
	v_mov_b32_e32 v70, v2
	v_mov_b32_e32 v71, v2
	v_mov_b32_e32 v72, v2
	v_mov_b32_e32 v73, v2
	v_mov_b32_e32 v74, v2
	v_mov_b32_e32 v75, v2
	v_mov_b32_e32 v76, v2
	v_mov_b32_e32 v77, v2
	v_mov_b32_e32 v78, v2
	v_mov_b32_e32 v79, v2
	v_mov_b32_e32 v80, v2
	v_mov_b32_e32 v81, v2
	v_mov_b32_e32 v82, v2
	v_mov_b32_e32 v83, v2
	v_mov_b32_e32 v84, v2
	v_mov_b32_e32 v85, v2
	v_mov_b32_e32 v86, v2
	v_mov_b32_e32 v87, v2
	v_mov_b32_e32 v88, v2
	v_mov_b32_e32 v89, v2
	v_mov_b32_e32 v90, v2
	v_mov_b32_e32 v91, v2
	v_mov_b32_e32 v92, v2
	v_mov_b32_e32 v93, v2
	v_mov_b32_e32 v94, v2
	v_mov_b32_e32 v95, v2
	v_mov_b32_e32 v96, v2
	v_mov_b32_e32 v97, v2
	v_mov_b32_e32 v34, v2
	v_mov_b32_e32 v35, v2
	v_mov_b32_e32 v36, v2
	v_mov_b32_e32 v37, v2
	v_mov_b32_e32 v38, v2
	v_mov_b32_e32 v39, v2
	v_mov_b32_e32 v40, v2
	v_mov_b32_e32 v41, v2
	v_mov_b32_e32 v42, v2
	v_mov_b32_e32 v43, v2
	v_mov_b32_e32 v44, v2
	v_mov_b32_e32 v45, v2
	v_mov_b32_e32 v46, v2
	v_mov_b32_e32 v47, v2
	v_mov_b32_e32 v48, v2
	v_mov_b32_e32 v49, v2
	v_mov_b32_e32 v50, v2
	v_mov_b32_e32 v51, v2
	v_mov_b32_e32 v52, v2
	v_mov_b32_e32 v53, v2
	v_mov_b32_e32 v54, v2
	v_mov_b32_e32 v55, v2
	v_mov_b32_e32 v56, v2
	v_mov_b32_e32 v57, v2
	v_mov_b32_e32 v58, v2
	v_mov_b32_e32 v59, v2
	v_mov_b32_e32 v60, v2
	v_mov_b32_e32 v61, v2
	v_mov_b32_e32 v62, v2
	v_mov_b32_e32 v63, v2
	v_mov_b32_e32 v64, v2
	v_mov_b32_e32 v65, v2
	v_mov_b32_e32 v98, v2
	v_mov_b32_e32 v99, v2
	v_mov_b32_e32 v100, v2
	v_mov_b32_e32 v101, v2
	v_mov_b32_e32 v102, v2
	v_mov_b32_e32 v103, v2
	v_mov_b32_e32 v104, v2
	v_mov_b32_e32 v105, v2
	v_mov_b32_e32 v106, v2
	v_mov_b32_e32 v107, v2
	v_mov_b32_e32 v108, v2
	v_mov_b32_e32 v109, v2
	v_mov_b32_e32 v110, v2
	v_mov_b32_e32 v111, v2
	v_mov_b32_e32 v112, v2
	v_mov_b32_e32 v113, v2
	v_mov_b32_e32 v114, v2
	v_mov_b32_e32 v115, v2
	v_mov_b32_e32 v116, v2
	v_mov_b32_e32 v117, v2
	v_mov_b32_e32 v118, v2
	v_mov_b32_e32 v119, v2
	v_mov_b32_e32 v120, v2
	v_mov_b32_e32 v121, v2
	v_mov_b32_e32 v122, v2
	v_mov_b32_e32 v123, v2
	v_mov_b32_e32 v124, v2
	v_mov_b32_e32 v125, v2
	v_mov_b32_e32 v126, v2
	v_mov_b32_e32 v127, v2
	v_mov_b32_e32 v128, v2
	v_mov_b32_e32 v129, v2
	.p2align	6

; #define PG8_STAGE(bufoff, gbase, voff) do { _Pragma("unroll") for (int _i = 0; _i < 2; ++_i) \
;         __builtin_amdgcn_global_load_lds((const unsigned*)((const char*)(gbase) + (voff)[_i]), (PG8_LAS unsigned*)(lds + (bufoff) + ldsw + _i * 8192), 16, 0, 0); } while (0)
; #define PG8_WAIT_V(n) asm volatile("s_waitcnt vmcnt(" #n ")" ::: "memory")
; #define PG8_BAR __builtin_amdgcn_s_barrier()
; template <class Epi, class Sched, bool ALIGN_EPI = false, bool SP2 = false>
; __device__ __forceinline__ void gemm_phase(PG8_LAS unsigned char* lds, const Gemm g, const Sched& S, const Epi& E) {
;     ...
;     f32x4 acc[2][2][4][2];
; #pragma unroll
;     for (int a = 0; a < 2; ++a)
; #pragma unroll
;         for (int b = 0; b < 2; ++b)
; #pragma unroll
;             for (int m = 0; m < 4; ++m)
; #pragma unroll
;                 for (int n = 0; n < 2; ++n) acc[a][b][m][n] = (f32x4){0.f, 0.f, 0.f, 0.f};
;     ...
;         PG8_STAGE(PG8_SB(0, 0), cB, voffB); PG8_STAGE(PG8_SB(0, 1), cB + hstep, voffB); PG8_STAGE(PG8_SA(0, 0), cA, voffA); PG8_STAGE(PG8_SA(0, 1), cA + hstep, voffA);
;         if (wr == 1) PG8_BAR;
;         PG8_WAIT_V(2); PG8_BAR;
;         PG8_STAGE(PG8_SB(1, 0), cB + kstep, voffB); PG8_STAGE(PG8_SA(1, 0), cA + kstep, voffA); PG8_STAGE(PG8_SB(1, 1), cB + hstep + kstep, voffB);
;         PG8_WAIT_V(6); PG8_BAR;
;     } else {
;         PG8_STAGE(PG8_SB(0, 0), cB, voffB); PG8_STAGE(PG8_SA(0, 0), cA, voffA); PG8_STAGE(PG8_SB(0, 1), cB + hstep, voffB); PG8_STAGE(PG8_SA(0, 1), cA + hstep, voffA);
;         if (wr == 1) PG8_BAR;
;         PG8_WAIT_V(4); PG8_BAR;
;         PG8_STAGE(PG8_SB(1, 0), cB + kstep, voffB); PG8_STAGE(PG8_SA(1, 0), cA + kstep, voffA); PG8_STAGE(PG8_SB(1, 1), cB + hstep + kstep, voffB);
;         PG8_WAIT_V(6); PG8_BAR;
.LBB0_632:
	v_lshl_add_u64 v[4:5], s[4:5], 0, v[0:1]
	v_mov_b32_e32 v135, v1
	s_add_i32 s57, s46, 0x18000
	v_lshl_add_u64 v[6:7], s[4:5], 0, v[134:135]
	v_mov_b32_e32 v131, v1
	v_bfe_u32 v140, v2, 4, 2
	v_and_b32_e32 v141, 15, v2
	v_lshl_add_u64 v[2:3], v[4:5], 0, s[50:51]
	s_mov_b32 m0, s57
	s_add_i32 s58, s46, 0x1a000
	v_lshl_add_u64 v[12:13], s[18:19], 0, v[130:131]
	v_mov_b32_e32 v133, v1
	s_waitcnt vmcnt(2)
	s_barrier
	global_load_lds_dwordx4 v[2:3], off
	v_lshl_add_u64 v[2:3], v[6:7], 0, s[50:51]
	s_mov_b32 m0, s58
	s_add_i32 s59, s46, 0x8000
	v_lshl_add_u64 v[14:15], s[18:19], 0, v[132:133]
	global_load_lds_dwordx4 v[2:3], off
	v_lshl_add_u64 v[2:3], v[12:13], 0, s[50:51]
	s_mov_b32 m0, s59
	s_add_i32 s60, s46, 0xa000
	v_lshl_add_u64 v[8:9], s[22:23], 0, v[0:1]
	global_load_lds_dwordx4 v[2:3], off
	v_lshl_add_u64 v[2:3], v[14:15], 0, s[50:51]
	s_mov_b32 m0, s60
	s_add_i32 s61, s46, 0x1c000
	v_lshl_add_u64 v[10:11], s[22:23], 0, v[134:135]
	global_load_lds_dwordx4 v[2:3], off
	v_lshl_add_u64 v[2:3], v[8:9], 0, s[50:51]
	s_mov_b32 m0, s61
	s_add_i32 s62, s46, 0x1e000
	global_load_lds_dwordx4 v[2:3], off
	v_lshl_add_u64 v[2:3], v[10:11], 0, s[50:51]
	s_mov_b32 m0, s62
	s_and_b32 s45, s45, 3
	global_load_lds_dwordx4 v[2:3], off
	s_waitcnt vmcnt(6)
	s_lshl_b32 s44, s70, 6
	v_mov_b32_e32 v129, 0
	s_cmp_lt_i32 s20, 64
	v_mov_b32_e32 v128, v129
	v_mov_b32_e32 v127, v129
	v_mov_b32_e32 v126, v129
	v_mov_b32_e32 v125, v129
	v_mov_b32_e32 v124, v129
	v_mov_b32_e32 v123, v129
	v_mov_b32_e32 v122, v129
	v_mov_b32_e32 v121, v129
	v_mov_b32_e32 v120, v129
	v_mov_b32_e32 v119, v129
	v_mov_b32_e32 v118, v129
	v_mov_b32_e32 v117, v129
	v_mov_b32_e32 v116, v129
	v_mov_b32_e32 v115, v129
	v_mov_b32_e32 v114, v129
	v_mov_b32_e32 v113, v129
	v_mov_b32_e32 v112, v129
	v_mov_b32_e32 v111, v129
	v_mov_b32_e32 v110, v129
	v_mov_b32_e32 v109, v129
	v_mov_b32_e32 v108, v129
	v_mov_b32_e32 v107, v129
	v_mov_b32_e32 v106, v129
	v_mov_b32_e32 v105, v129
	v_mov_b32_e32 v104, v129
	v_mov_b32_e32 v103, v129
	v_mov_b32_e32 v102, v129
	v_mov_b32_e32 v101, v129
	v_mov_b32_e32 v100, v129
	v_mov_b32_e32 v99, v129
	v_mov_b32_e32 v98, v129
	v_mov_b32_e32 v65, v129
	v_mov_b32_e32 v64, v129
	v_mov_b32_e32 v63, v129
	v_mov_b32_e32 v62, v129
	v_mov_b32_e32 v61, v129
	v_mov_b32_e32 v60, v129
	v_mov_b32_e32 v59, v129
	v_mov_b32_e32 v58, v129
	v_mov_b32_e32 v57, v129
	v_mov_b32_e32 v56, v129
	v_mov_b32_e32 v55, v129
	v_mov_b32_e32 v54, v129
	v_mov_b32_e32 v53, v129
	v_mov_b32_e32 v52, v129
	v_mov_b32_e32 v51, v129
	v_mov_b32_e32 v50, v129
	v_mov_b32_e32 v49, v129
	v_mov_b32_e32 v48, v129
	v_mov_b32_e32 v47, v129
	v_mov_b32_e32 v46, v129
	v_mov_b32_e32 v45, v129
	v_mov_b32_e32 v44, v129
	v_mov_b32_e32 v43, v129
	v_mov_b32_e32 v42, v129
	v_mov_b32_e32 v41, v129
	v_mov_b32_e32 v40, v129
	v_mov_b32_e32 v39, v129
	v_mov_b32_e32 v38, v129
	v_mov_b32_e32 v37, v129
	v_mov_b32_e32 v36, v129
	v_mov_b32_e32 v35, v129
	v_mov_b32_e32 v34, v129
	v_mov_b32_e32 v97, v129
	v_mov_b32_e32 v96, v129
	v_mov_b32_e32 v95, v129
	v_mov_b32_e32 v94, v129
	v_mov_b32_e32 v93, v129
	v_mov_b32_e32 v92, v129
	v_mov_b32_e32 v91, v129
	v_mov_b32_e32 v90, v129
	v_mov_b32_e32 v89, v129
	v_mov_b32_e32 v88, v129
	v_mov_b32_e32 v87, v129
	v_mov_b32_e32 v86, v129
	v_mov_b32_e32 v85, v129
	v_mov_b32_e32 v84, v129
	v_mov_b32_e32 v83, v129
	v_mov_b32_e32 v82, v129
	v_mov_b32_e32 v81, v129
	v_mov_b32_e32 v80, v129
	v_mov_b32_e32 v79, v129
	v_mov_b32_e32 v78, v129
	v_mov_b32_e32 v77, v129
	v_mov_b32_e32 v76, v129
	v_mov_b32_e32 v75, v129
	v_mov_b32_e32 v74, v129
	v_mov_b32_e32 v73, v129
	v_mov_b32_e32 v72, v129
	v_mov_b32_e32 v71, v129
	v_mov_b32_e32 v70, v129
	v_mov_b32_e32 v69, v129
	v_mov_b32_e32 v68, v129
	v_mov_b32_e32 v67, v129
	v_mov_b32_e32 v66, v129
	v_mov_b32_e32 v33, v129
	v_mov_b32_e32 v32, v129
	v_mov_b32_e32 v31, v129
	v_mov_b32_e32 v30, v129
	v_mov_b32_e32 v29, v129
	v_mov_b32_e32 v28, v129
	v_mov_b32_e32 v27, v129
	v_mov_b32_e32 v26, v129
	v_mov_b32_e32 v25, v129
	v_mov_b32_e32 v24, v129
	v_mov_b32_e32 v23, v129
	v_mov_b32_e32 v22, v129
	v_mov_b32_e32 v21, v129
	v_mov_b32_e32 v20, v129
	v_mov_b32_e32 v19, v129
	v_mov_b32_e32 v18, v129
	v_mov_b32_e32 v17, v129
	v_mov_b32_e32 v16, v129
	v_mov_b32_e32 v15, v129
	v_mov_b32_e32 v14, v129
	v_mov_b32_e32 v13, v129
	v_mov_b32_e32 v12, v129
	v_mov_b32_e32 v11, v129
	v_mov_b32_e32 v10, v129
	v_mov_b32_e32 v9, v129
	v_mov_b32_e32 v8, v129
	v_mov_b32_e32 v7, v129
	v_mov_b32_e32 v6, v129
	v_mov_b32_e32 v5, v129
	v_mov_b32_e32 v4, v129
	v_mov_b32_e32 v3, v129
	v_mov_b32_e32 v2, v129
	s_barrier
; DI int tid8_op() { int t = threadIdx.x; asm volatile("" : "+v"(t)); return t; }
; template <class Epi, class Sched, bool ALIGN_EPI = false, bool SP2 = false>
; __device__ __forceinline__ void gemm_phase(PG8_LAS unsigned char* lds, const Gemm g, const Sched& S, const Epi& E) {
;     const int tid = ::tid8_op(), wid = __builtin_amdgcn_readfirstlane(tid >> 6), lane = tid & 63, wr = wid >> 2, wc = wid & 3, fr = lane & 15, fq = lane >> 4;
;     const int K = g.K, nt = K / BK;
;     unsigned voffA[2], voffB[2];
; #pragma unroll
;     for (int i = 0; i < 2; ++i) { int R, C; stage_rc(tid * 16 + i * 8192, R, C); const int Rb = Epi::PERM ? ((R & ~31) + perm32(R & 31)) : R;
;         voffA[i] = (unsigned)(R * K + C) * 2u; voffB[i] = (unsigned)(Rb * K + C) * 2u; }
;     const size_t kstep = (size_t)(BK * 2);
;     const size_t hstep = (size_t)HALF * K * 2;
;     const size_t tstep = 2 * hstep;
;     const unsigned ldsw = (unsigned)wid * 1024u;
;     const int aoff = lds_byte(wr * 64 + fr, fq * 8), boff = lds_byte(wc * 32 + fr, fq * 8);
;     ...
;     f32x4 acc[2][2][4][2];
; #pragma unroll
;     for (int a = 0; a < 2; ++a)
; #pragma unroll
;         for (int b = 0; b < 2; ++b)
; #pragma unroll
;             for (int m = 0; m < 4; ++m)
; #pragma unroll
;                 for (int n = 0; n < 2; ++n) acc[a][b][m][n] = (f32x4){0.f, 0.f, 0.f, 0.f};
;     bf16x8 At[4][2], B0[2][2], B1[2][2];
;     const char* cA = (const char*)g.A + (size_t)cur.pm * tstep; const char* cB = (const char*)g.Bt + (size_t)cur.pn * tstep;
	s_cbranch_scc1 .LBB0_635
	s_lshr_b32 s22, s21, 26
	s_add_i32 s22, s20, s22
	v_or_b32_e32 v2, s44, v141
	s_ashr_i32 s66, s22, 6
	v_lshlrev_b32_e32 v3, 4, v140
	v_lshlrev_b32_e32 v4, 6, v2
	s_movk_i32 s22, 0x3c0
	v_lshlrev_b32_e32 v2, 2, v2
	v_and_or_b32 v4, v4, s22, v3
	s_lshl_b32 s22, s70, 13
	v_and_b32_e32 v2, 32, v2
	v_bitop3_b32 v142, v4, s22, v2 bitop3:0xde
	v_lshl_or_b32 v2, v141, 6, v3
	v_lshlrev_b32_e32 v3, 2, v141
	s_lshl_b32 s22, s45, 12
	v_and_b32_e32 v3, 32, v3
	v_bitop3_b32 v143, v2, s22, v3 bitop3:0xde
	s_lshl_b64 s[22:23], s[16:17], 9
	s_or_b32 s17, s22, 0x100
	s_mul_i32 s21, s17, s21
	s_mul_hi_u32 s22, s17, s20
	s_add_i32 s21, s22, s21
	s_mul_i32 s22, s23, s20
	s_add_i32 s69, s66, -2
	s_add_i32 s21, s21, s22
	s_mul_i32 s17, s17, s20
	v_add_u32_e32 v2, v145, v136
	s_add_u32 s20, s8, s17
	v_add_lshl_u32 v2, v2, v137, 1
	v_mov_b32_e32 v3, v1
	s_addc_u32 s21, s9, s21
	v_lshl_add_u64 v[136:137], s[20:21], 0, v[2:3]
	v_add_u32_e32 v2, v144, v138
	v_add_lshl_u32 v2, v2, v139, 1
	v_lshl_add_u64 v[138:139], s[20:21], 0, v[2:3]
	v_mov_b32_e32 v2, 0
	s_mov_b32 s17, 0
	s_mov_b64 s[20:21], 0x9080080
	v_mov_b32_e32 v3, v2
	v_mov_b32_e32 v4, v2
	v_mov_b32_e32 v5, v2
	v_mov_b32_e32 v6, v2
	v_mov_b32_e32 v7, v2
	v_mov_b32_e32 v8, v2
	v_mov_b32_e32 v9, v2
	v_mov_b32_e32 v10, v2
	v_mov_b32_e32 v11, v2
	v_mov_b32_e32 v12, v2
	v_mov_b32_e32 v13, v2
	v_mov_b32_e32 v14, v2
	v_mov_b32_e32 v15, v2
	v_mov_b32_e32 v16, v2
	v_mov_b32_e32 v17, v2
	v_mov_b32_e32 v18, v2
	v_mov_b32_e32 v19, v2
	v_mov_b32_e32 v20, v2
	v_mov_b32_e32 v21, v2
	v_mov_b32_e32 v22, v2
	v_mov_b32_e32 v23, v2
	v_mov_b32_e32 v24, v2
	v_mov_b32_e32 v25, v2
	v_mov_b32_e32 v26, v2
	v_mov_b32_e32 v27, v2
	v_mov_b32_e32 v28, v2
	v_mov_b32_e32 v29, v2
	v_mov_b32_e32 v30, v2
	v_mov_b32_e32 v31, v2
	v_mov_b32_e32 v32, v2
	v_mov_b32_e32 v33, v2
	v_mov_b32_e32 v66, v2
	v_mov_b32_e32 v67, v2
	v_mov_b32_e32 v68, v2
	v_mov_b32_e32 v69, v2
	v_mov_b32_e32 v70, v2
	v_mov_b32_e32 v71, v2
	v_mov_b32_e32 v72, v2
	v_mov_b32_e32 v73, v2
	v_mov_b32_e32 v74, v2
	v_mov_b32_e32 v75, v2
	v_mov_b32_e32 v76, v2
	v_mov_b32_e32 v77, v2
	v_mov_b32_e32 v78, v2
	v_mov_b32_e32 v79, v2
	v_mov_b32_e32 v80, v2
	v_mov_b32_e32 v81, v2
	v_mov_b32_e32 v82, v2
	v_mov_b32_e32 v83, v2
	v_mov_b32_e32 v84, v2
	v_mov_b32_e32 v85, v2
	v_mov_b32_e32 v86, v2
	v_mov_b32_e32 v87, v2
	v_mov_b32_e32 v88, v2
	v_mov_b32_e32 v89, v2
	v_mov_b32_e32 v90, v2
	v_mov_b32_e32 v91, v2
	v_mov_b32_e32 v92, v2
	v_mov_b32_e32 v93, v2
	v_mov_b32_e32 v94, v2
	v_mov_b32_e32 v95, v2
	v_mov_b32_e32 v96, v2
	v_mov_b32_e32 v97, v2
	v_mov_b32_e32 v34, v2
	v_mov_b32_e32 v35, v2
	v_mov_b32_e32 v36, v2
	v_mov_b32_e32 v37, v2
	v_mov_b32_e32 v38, v2
	v_mov_b32_e32 v39, v2
	v_mov_b32_e32 v40, v2
	v_mov_b32_e32 v41, v2
	v_mov_b32_e32 v42, v2
	v_mov_b32_e32 v43, v2
	v_mov_b32_e32 v44, v2
	v_mov_b32_e32 v45, v2
	v_mov_b32_e32 v46, v2
	v_mov_b32_e32 v47, v2
	v_mov_b32_e32 v48, v2
	v_mov_b32_e32 v49, v2
	v_mov_b32_e32 v50, v2
	v_mov_b32_e32 v51, v2
	v_mov_b32_e32 v52, v2
	v_mov_b32_e32 v53, v2
	v_mov_b32_e32 v54, v2
	v_mov_b32_e32 v55, v2
	v_mov_b32_e32 v56, v2
	v_mov_b32_e32 v57, v2
	v_mov_b32_e32 v58, v2
	v_mov_b32_e32 v59, v2
	v_mov_b32_e32 v60, v2
	v_mov_b32_e32 v61, v2
	v_mov_b32_e32 v62, v2
	v_mov_b32_e32 v63, v2
	v_mov_b32_e32 v64, v2
	v_mov_b32_e32 v65, v2
	v_mov_b32_e32 v98, v2
	v_mov_b32_e32 v99, v2
	v_mov_b32_e32 v100, v2
	v_mov_b32_e32 v101, v2
	v_mov_b32_e32 v102, v2
	v_mov_b32_e32 v103, v2
	v_mov_b32_e32 v104, v2
	v_mov_b32_e32 v105, v2
	v_mov_b32_e32 v106, v2
	v_mov_b32_e32 v107, v2
	v_mov_b32_e32 v108, v2
	v_mov_b32_e32 v109, v2
	v_mov_b32_e32 v110, v2
	v_mov_b32_e32 v111, v2
	v_mov_b32_e32 v112, v2
	v_mov_b32_e32 v113, v2
	v_mov_b32_e32 v114, v2
	v_mov_b32_e32 v115, v2
	v_mov_b32_e32 v116, v2
	v_mov_b32_e32 v117, v2
	v_mov_b32_e32 v118, v2
	v_mov_b32_e32 v119, v2
	v_mov_b32_e32 v120, v2
	v_mov_b32_e32 v121, v2
	v_mov_b32_e32 v122, v2
	v_mov_b32_e32 v123, v2
	v_mov_b32_e32 v124, v2
	v_mov_b32_e32 v125, v2
	v_mov_b32_e32 v126, v2
	v_mov_b32_e32 v127, v2
	v_mov_b32_e32 v128, v2
	v_mov_b32_e32 v129, v2
	.p2align	6

; DI unsigned pk2(float a, float b) { f32x2 v = {a, b}; return __builtin_bit_cast(unsigned, __builtin_convertvector(v, bf2_t)); }
; DI float bflo(unsigned u) { return __uint_as_float(u << 16); }
; DI float bfhi(unsigned u) { return __uint_as_float(u & 0xffff0000u); }
;     ...
; #pragma unroll
;     for (int nt = 0; nt < 2; ++nt)
; #pragma unroll
;         for (int qd = 0; qd < 4; ++qd) {
;             const u32x2 g = gv[nt][qd];
;             const f32x16& o = nt ? o1 : o0;
;             u32x2 v;
;             v.x = pk2(o[4 * qd] * bflo(g.x), o[4 * qd + 1] * bfhi(g.x));
;             v.y = pk2(o[4 * qd + 2] * bflo(g.y), o[4 * qd + 3] * bfhi(g.y));
;             *(u32x2*)(yrow + 32 * nt + 8 * qd) = v;
;         }
; DI void phase3(const Params& p, int l, unsigned char* smem, unsigned char* smem0) {
;     ...
;     while (true) {
;         __syncthreads();
;         if (threadIdx.x == 0) {
;             int code = -1;
;             while (vict < 8) {
;                 const int x = (myx + vict) & 7;
;                 const unsigned idx = atomicAdd(cnt + x, 1u);
;                 if (idx < 256u) { code = x * 256 + (int)idx; break; }
;                 ++vict;
;             }
;             *s_item = code;
;         }
;         __syncthreads();
;         const int code = *s_item;
;         if (code < 0) break;
.LBB0_710:
	s_mov_b32 s93, 0xfffffc0
	s_mov_b32 s94, 0x800000
	.p2align	6
.LBB0_711:
	v_lshlrev_b32_e32 v18, 16, v40
	v_and_b32_e32 v19, 0xffff0000, v40
	v_pk_mul_f32 v[2:3], v[2:3], v[18:19]
	v_lshlrev_b32_e32 v18, 16, v41
	v_and_b32_e32 v19, 0xffff0000, v41
	v_pk_mul_f32 v[4:5], v[4:5], v[18:19]
	v_cvt_pk_bf16_f32 v2, v2, v3
	v_cvt_pk_bf16_f32 v3, v4, v5
	global_store_dwordx2 v[42:43], v[2:3], off offset:64
	v_lshlrev_b32_e32 v2, 16, v38
	v_and_b32_e32 v3, 0xffff0000, v38
	v_lshlrev_b32_e32 v4, 16, v39
	v_and_b32_e32 v5, 0xffff0000, v39
	v_pk_mul_f32 v[2:3], v[6:7], v[2:3]
	v_pk_mul_f32 v[4:5], v[8:9], v[4:5]
	v_cvt_pk_bf16_f32 v2, v2, v3
	v_cvt_pk_bf16_f32 v3, v4, v5
	global_store_dwordx2 v[42:43], v[2:3], off offset:80
	v_lshlrev_b32_e32 v2, 16, v36
	v_and_b32_e32 v3, 0xffff0000, v36
	v_lshlrev_b32_e32 v4, 16, v37
	v_and_b32_e32 v5, 0xffff0000, v37
	v_pk_mul_f32 v[2:3], v[10:11], v[2:3]
	v_pk_mul_f32 v[4:5], v[12:13], v[4:5]
	v_cvt_pk_bf16_f32 v2, v2, v3
	v_cvt_pk_bf16_f32 v3, v4, v5
	global_store_dwordx2 v[42:43], v[2:3], off offset:96
	v_lshlrev_b32_e32 v2, 16, v34
	v_and_b32_e32 v3, 0xffff0000, v34
	v_lshlrev_b32_e32 v4, 16, v35
	v_and_b32_e32 v5, 0xffff0000, v35
	v_pk_mul_f32 v[2:3], v[14:15], v[2:3]
	v_pk_mul_f32 v[4:5], v[16:17], v[4:5]
	v_cvt_pk_bf16_f32 v2, v2, v3
	v_cvt_pk_bf16_f32 v3, v4, v5
	global_store_dwordx2 v[42:43], v[2:3], off offset:112
	.p2align	6

; DI void phase3(const Params& p, int l, unsigned char* smem, unsigned char* smem0) {
;     ...
;     while (true) {
;         __syncthreads();
;         if (threadIdx.x == 0) {
;             int code = -1;
;             while (vict < 8) {
;                 const int x = (myx + vict) & 7;
;                 const unsigned idx = atomicAdd(cnt + x, 1u);
;                 if (idx < 256u) { code = x * 256 + (int)idx; break; }
;                 ++vict;
;             }
;             *s_item = code;
;         }
;         __syncthreads();
;         const int code = *s_item;
;         if (code < 0) break;
;         const int x = code >> 8, idx = code & 255, bh = x + 8 * hf, b = bh >> 2, head = bh & 3;
;         if (idx < 192) {
;             const int qb = 63 - idx / 3, r3 = idx % 3, br = (r3 == 0) ? 1 : (r3 == 1 ? 2 : 0), q0 = qb * 128, nt = 2 * qb + 2;
;             if (br == 0) {
;                 attn_item<64, 1, true>((const bf16_t*)(ws + O_SBQ) + ((size_t)bh * S_ + q0) * 64, (const bf16_t*)(ws + O_SBK) + (size_t)bh * S_ * 64,
;                                  (const bf16_t*)(ws + O_SBVT) + (size_t)bh * 64 * S_, S_, nullptr, q0, nt, GATE + ((size_t)b * S_ + q0) * 1024 + 256 + head * 64, YBo + ((size_t)b * S_ + q0) * 1024 + 256 + head * 64, smem, smem0, hf);
;             } else if (br == 1) {
;                 attn_item<96, 0, false>((const bf16_t*)(ws + O_MQ) + ((size_t)bh * S_ + q0) * 96, (const bf16_t*)(ws + O_MK) + (size_t)bh * S_ * 96,
;                                  (const bf16_t*)(ws + O_MVT) + (size_t)bh * 64 * S_, S_, nullptr, q0, nt, GATE + ((size_t)b * S_ + q0) * 1024 + head * 64, YBo + ((size_t)b * S_ + q0) * 1024 + head * 64, smem, smem0, hf);
;             } else {
;                 attn_item<64, 0, true>((const bf16_t*)(ws + O_FQ) + ((size_t)bh * S_ + q0) * 64, (const bf16_t*)(ws + O_FK) + (size_t)bh * S_ * 64,
;                                  (const bf16_t*)(ws + O_FVT) + (size_t)bh * 64 * S_, S_, (const float*)(ws + O_FC) + (size_t)bh * S_, q0, nt,
;                                  GATE + ((size_t)b * S_ + q0) * 1024 + 512 + head * 64, YBo + ((size_t)b * S_ + q0) * 1024 + 512 + head * 64, smem, smem0, hf,
;                                  sqrtf(((const float*)(ws + O_KMAX))[bh]) * 1.0002f);
;             }
;         } else {
;             const int qb = idx - 192, q0 = qb * 128;
.LBB0_720:
	s_or_b64 exec, exec, s[4:5]
	s_waitcnt lgkmcnt(0)
	s_barrier
	ds_read_b32 v0, v219
	s_waitcnt lgkmcnt(0)
	v_cmp_gt_i32_e32 vcc, 0, v0
	v_readfirstlane_b32 s8, v0
	s_cbranch_vccnz .LBB0_730
	s_lshr_b32 s4, s8, 8
	s_add_i32 s10, s4, s72
	s_and_b32 s9, s8, 0xff
	s_lshr_b32 s56, s10, 2
	s_bfe_u32 s79, s8, 0x20008
	s_cmpk_gt_u32 s9, 0xbf
	s_mov_b64 s[4:5], -1
	s_cbranch_scc0 .LBB0_732
	s_lshl_b32 s4, s9, 7
	s_mov_b32 s11, s49
	s_add_i32 s48, s4, 0xffffa000
	s_lshl_b64 s[4:5], s[10:11], 20
	s_add_u32 s6, s73, s4
	s_addc_u32 s7, s74, s5
	s_lshl_b64 s[4:5], s[48:49], 7
	s_add_u32 s6, s6, s4
	s_addc_u32 s7, s7, s5
	s_lshl_b64 s[4:5], s[10:11], 15
	v_mov_b32_e32 v14, v215
	s_add_u32 s12, s75, s4
	s_addc_u32 s13, s87, s5
	v_lshlrev_b32_e32 v2, 4, v14
	v_lshlrev_b32_e32 v0, 6, v14
	v_and_b32_e32 v3, 0x70, v2
	s_movk_i32 s11, 0xfe00
	s_add_u32 s14, s62, s4
	v_and_or_b32 v4, v0, s11, v3
	v_mov_b32_e32 v3, v1
	v_add_u32_e32 v8, 0x1000, v2
	v_mov_b32_e32 v9, v1
	v_ashrrev_i32_e32 v0, 1, v14
	s_addc_u32 s15, s3, s5
	v_lshl_add_u64 v[6:7], s[12:13], 0, v[2:3]
	v_lshl_add_u64 v[10:11], s[12:13], 0, v[8:9]
	v_mov_b32_e32 v5, v1
	v_bfi_b32 v98, s41, v0, v14
	global_load_dwordx4 v[66:69], v[6:7], off
	global_load_dwordx4 v[70:73], v[10:11], off
	v_lshl_add_u64 v[6:7], s[14:15], 0, v[4:5]
	v_add_u32_e32 v10, 0x4000, v4
	v_mov_b32_e32 v11, v1
	v_ashrrev_i32_e32 v99, 31, v98
	v_lshl_add_u64 v[12:13], s[14:15], 0, v[10:11]
	global_load_dwordx4 v[74:77], v[6:7], off
	global_load_dwordx4 v[78:81], v[12:13], off
	v_bfe_u32 v101, v14, 5, 1
	v_lshlrev_b64 v[6:7], 7, v[98:99]
	v_lshl_add_u64 v[6:7], s[6:7], 0, v[6:7]
	v_lshlrev_b32_e32 v0, 4, v101
	v_lshl_add_u64 v[6:7], v[6:7], 0, v[0:1]
	global_load_dwordx4 v[82:85], v[6:7], off
	global_load_dwordx4 v[86:89], v[6:7], off offset:32
	global_load_dwordx4 v[90:93], v[6:7], off offset:64
	global_load_dwordx4 v[94:97], v[6:7], off offset:96
	v_ashrrev_i32_e32 v7, 31, v14
	v_add_u32_e32 v12, 0x100, v14
	v_and_b32_e32 v6, 31, v14
	v_lshrrev_b32_e32 v13, 3, v14
	v_lshlrev_b32_e32 v15, 3, v14
	v_lshrrev_b32_e32 v7, 29, v7
	v_ashrrev_i32_e32 v16, 31, v12
	s_movk_i32 s0, 0x48
	v_and_b32_e32 v15, 56, v15
	v_mul_lo_u32 v13, v13, s0
	v_lshrrev_b32_e32 v17, 3, v12
	v_mul_u32_u24_e32 v6, 0x48, v6
	v_add_u32_e32 v7, v14, v7
	v_lshrrev_b32_e32 v16, 29, v16
	v_lshlrev_b32_e32 v111, 1, v13
	v_lshlrev_b32_e32 v112, 1, v15
	v_mul_lo_u32 v13, v17, s0
	v_lshlrev_b32_e32 v6, 1, v6
	v_lshrrev_b32_e32 v15, 3, v7
	v_and_b32_e32 v7, -8, v7
	v_add_u32_e32 v16, v12, v16
	v_lshlrev_b32_e32 v113, 1, v13
	v_add3_u32 v114, s33, v6, v0
	v_sub_u32_e32 v0, v14, v7
	v_mul_lo_u32 v6, v15, s0
	v_lshrrev_b32_e32 v7, 3, v16
	v_and_b32_e32 v13, -8, v16
	v_lshlrev_b32_e32 v16, 3, v0
	v_lshlrev_b32_e32 v115, 1, v6
	v_lshlrev_b32_e32 v0, 4, v0
	v_sub_u32_e32 v6, v12, v13
	v_mul_lo_u32 v7, v7, s0
	v_add3_u32 v14, s33, v113, v112
	v_add3_u32 v0, s33, v115, v0
	v_lshlrev_b32_e32 v18, 3, v6
	v_lshlrev_b32_e32 v116, 1, v7
	v_lshlrev_b32_e32 v6, 4, v6
	v_add3_u32 v17, s33, v111, v112
	v_add3_u32 v6, s33, v116, v6
	s_waitcnt lgkmcnt(0)
	s_barrier
	v_mov_b32_e32 v15, v1
	v_lshl_add_u64 v[102:103], s[52:53], 0, v[10:11]
	v_lshl_add_u64 v[104:105], s[52:53], 0, v[4:5]
	v_lshl_add_u64 v[106:107], s[54:55], 0, v[8:9]
	v_lshl_add_u64 v[108:109], s[54:55], 0, v[2:3]
	v_mov_b32_e32 v2, v1
	v_mov_b32_e32 v4, v1
	s_waitcnt vmcnt(0)
	ds_write_b128 v0, v[66:69]
	ds_write_b128 v6, v[70:73]
	ds_write_b128 v17, v[74:77] offset:13312
	ds_write_b128 v14, v[78:81] offset:13312
	v_mov_b32_e32 v14, v1
	v_mov_b32_e32 v0, v1
	v_mov_b32_e32 v6, v1
	v_mov_b32_e32 v7, v1
	v_mov_b32_e32 v8, v1
	v_mov_b32_e32 v10, v1
	v_mov_b32_e32 v12, v1
	v_mov_b32_e32 v13, v1
	v_lshlrev_b32_e32 v119, 1, v18
	v_mov_b64_e32 v[32:33], v[14:15]
	v_lshlrev_b32_e32 v100, 3, v101
	v_lshlrev_b32_e32 v118, 1, v16
	v_mov_b64_e32 v[30:31], v[12:13]
	v_mov_b64_e32 v[28:29], v[10:11]
	v_mov_b64_e32 v[26:27], v[8:9]
	v_mov_b64_e32 v[24:25], v[6:7]
	v_mov_b64_e32 v[22:23], v[4:5]
	v_mov_b64_e32 v[20:21], v[2:3]
	v_mov_b64_e32 v[18:19], v[0:1]
	v_mov_b64_e32 v[16:17], v[14:15]
	s_mov_b32 s11, 0
	v_sub_u32_e32 v117, 0, v100
	v_mov_b32_e32 v120, 0
	v_mov_b32_e32 v110, 0xff800000
	v_mov_b64_e32 v[14:15], v[12:13]
	v_mov_b64_e32 v[12:13], v[10:11]
	v_mov_b64_e32 v[10:11], v[8:9]
	v_mov_b64_e32 v[8:9], v[6:7]
	v_mov_b64_e32 v[6:7], v[4:5]
	v_mov_b64_e32 v[4:5], v[2:3]
	v_mov_b64_e32 v[2:3], v[0:1]
	s_cmp_lg_u32 s11, 3
	s_cselect_b64 s[6:7], -1, 0
	s_cmp_eq_u32 s11, 3
	s_cbranch_scc1 .LBB0_724
	.p2align	6
.LBB0_723:
	v_lshl_add_u64 v[34:35], v[108:109], 0, s[4:5]
	s_waitcnt vmcnt(0)
	global_load_dwordx4 v[66:69], v[34:35], off
	v_lshl_add_u64 v[34:35], v[106:107], 0, s[4:5]
	global_load_dwordx4 v[70:73], v[34:35], off
	v_lshl_add_u64 v[34:35], v[104:105], 0, s[4:5]
	global_load_dwordx4 v[74:77], v[34:35], off
	v_lshl_add_u64 v[34:35], v[102:103], 0, s[4:5]
	global_load_dwordx4 v[78:81], v[34:35], off
	.p2align	6

;     ...
;     auto st_tile = [&](int buf) {
;         bf16_t* sK = (bf16_t*)(smem + buf * ATT_BUF); bf16_t* sV = (bf16_t*)(smem + buf * ATT_BUF + 13312); float* sC = (float*)(smem + buf * ATT_BUF + 22528);
; #pragma unroll
;         for (int j = 0; j < NKL; ++j) { const int c = tid + 256 * j, row = c / KCH, kc = (c % KCH) * 8; *(u32x4*)(sK + row * KS + kc) = rk[j]; }
; #pragma unroll
;         for (int j = 0; j < 2; ++j) { const int c = tid + 256 * j, row = c >> 3, kc = (c & 7) * 8; *(u32x4*)(sV + row * LS + kc) = rv[j]; }
;         if (cdec && tid < 16) *(f32x4*)(sC + 4 * tid) = rc;
;     ...
;         if (MODE == 1) {
;             const int done = (__builtin_amdgcn_ballot_w64(R != 0.f) == 0) ? 1 : 0;
;             if (lane == 0) ((int*)(smem0 + SMEM_FLAG))[(it & 1) * 8 + hf * 4 + w] = done;
;         }
;         if (MODE == 0 && DESC) {
;             const float ncl = (kt > 0) ? cdec[64 * kt - 1] : 0.f;
;             const bool live = !(qn + ncl - m < -152.f);
;             const int done = (__builtin_amdgcn_ballot_w64(live) == 0) ? 1 : 0;
;             if (lane == 0) ((int*)(smem0 + SMEM_FLAG))[(it & 1) * 8 + hf * 4 + w] = done;
;         }
;         if (it + 1 < ntiles) st_tile(buf ^ 1);
.LBB0_793:
	s_andn2_b64 vcc, exec, s[8:9]
	s_mov_b64 s[8:9], 0
	s_cbranch_vccnz .LBB0_799
	s_add_i32 s8, s92, 64
	s_and_b32 s93, s10, 1
	v_cmp_lt_i32_e32 vcc, s8, v131
	s_and_saveexec_b64 s[58:59], vcc
	s_cbranch_execnz .LBB0_802
	s_or_b64 exec, exec, s[58:59]
	v_cmp_neq_f32_e32 vcc, 0, v109
	s_and_saveexec_b64 s[8:9], s[6:7]
	s_cbranch_execnz .LBB0_805
	.p2align	6
.LBB0_796:
	s_or_b64 exec, exec, s[8:9]
	s_andn2_b64 vcc, exec, s[44:45]
	s_cbranch_vccnz .LBB0_798
	.p2align	6
.LBB0_797:
	s_xor_b32 s8, s93, 1
	s_mulk_i32 s8, 0x5900
	s_add_i32 s8, s33, s8
	v_add3_u32 v34, s8, v129, v135
	s_waitcnt vmcnt(0)
	ds_write_b128 v34, v[66:69]
	v_add3_u32 v34, s8, v130, v136
	ds_write_b128 v34, v[70:73]
	v_add3_u32 v34, s8, v125, v126
	ds_write_b128 v34, v[90:93] offset:13312
	v_add3_u32 v34, s8, v128, v126
	ds_write_b128 v34, v[94:97] offset:13312
	.p2align	6

; #define PG8_LAS __attribute__((address_space(3)))
; #define PG8_STAGE(bufoff, gbase, voff) do { _Pragma("unroll") for (int _i = 0; _i < 2; ++_i) \
;         __builtin_amdgcn_global_load_lds((const unsigned*)((const char*)(gbase) + (voff)[_i]), (PG8_LAS unsigned*)(lds + (bufoff) + ldsw + _i * 8192), 16, 0, 0); } while (0)
; #define PG8_WAIT_V(n) asm volatile("s_waitcnt vmcnt(" #n ")" ::: "memory")
; #define PG8_BAR __builtin_amdgcn_s_barrier()
; template <class Epi, class Sched, bool ALIGN_EPI = false, bool SP2 = false>
; __device__ __forceinline__ void gemm_phase(PG8_LAS unsigned char* lds, const Gemm g, const Sched& S, const Epi& E) {
;     ...
;         PG8_STAGE(PG8_SB(0, 0), cB, voffB); PG8_STAGE(PG8_SB(0, 1), cB + hstep, voffB); PG8_STAGE(PG8_SA(0, 0), cA, voffA); PG8_STAGE(PG8_SA(0, 1), cA + hstep, voffA);
;         if (wr == 1) PG8_BAR;
;         PG8_WAIT_V(2); PG8_BAR;
;         PG8_STAGE(PG8_SB(1, 0), cB + kstep, voffB); PG8_STAGE(PG8_SA(1, 0), cA + kstep, voffA); PG8_STAGE(PG8_SB(1, 1), cB + hstep + kstep, voffB);
;         PG8_WAIT_V(6); PG8_BAR;
;     } else {
;         PG8_STAGE(PG8_SB(0, 0), cB, voffB); PG8_STAGE(PG8_SA(0, 0), cA, voffA); PG8_STAGE(PG8_SB(0, 1), cB + hstep, voffB); PG8_STAGE(PG8_SA(0, 1), cA + hstep, voffA);
;         if (wr == 1) PG8_BAR;
;         PG8_WAIT_V(4); PG8_BAR;
;         PG8_STAGE(PG8_SB(1, 0), cB + kstep, voffB); PG8_STAGE(PG8_SA(1, 0), cA + kstep, voffA); PG8_STAGE(PG8_SB(1, 1), cB + hstep + kstep, voffB);
;         PG8_WAIT_V(6); PG8_BAR;
; DI void phase5(const Params& p, int l, unsigned char* smem) {
;     unsigned char* ws = p.ws; asm volatile("" : "+s"(ws));
;     pg8::Gemm g; g.A = (const bf16_t*)(ws + O_XB); g.Bt = (const bf16_t*)(ws + O_WOUT + l * SZ_WOUT); g.M = T_; g.N = 1024; g.K = 1024;
;     pg8::StaticOrder S; S.init(T_, 1024, (int)gridDim.x, (int)blockIdx.x);
;     EpiP5 E; E.x = p.x; E.out = p.out; E.st = (const float*)(ws + O_STATS); E.lg = p.ln_g + (l > 0 ? (l - 1) * 1024 : 0); E.lb = p.ln_b + (l > 0 ? (l - 1) * 1024 : 0); E.l = l;
;     pg8::gemm_phase<EpiP5, pg8::StaticOrder, true, true>((PG8_LAS unsigned char*)smem, g, S, E);
.LBB0_939:
	s_add_u32 s80, s4, 0x1a080000
	s_addc_u32 s81, s5, 0
	s_cmp_eq_u32 s10, 0
	s_cselect_b64 s[4:5], -1, 0
	s_cmp_lg_u32 s10, 0
	s_cselect_b64 s[86:87], -1, 0
	s_add_i32 s16, s36, 0xfffffc00
	s_and_b64 s[14:15], s[4:5], exec
	s_cselect_b32 s48, 0, s16
	v_readlane_b32 s12, v253, 0
	s_lshl_b64 s[8:9], s[48:49], 2
	v_readlane_b32 s22, v253, 10
	v_readlane_b32 s23, v253, 11
	s_add_u32 s92, s22, s8
	v_readlane_b32 s24, v253, 12
	s_addc_u32 s93, s23, s9
	v_readlane_b32 s19, v253, 7
	v_readlane_b32 s25, v253, 13
	s_add_u32 s94, s24, s8
	v_lshrrev_b32_e32 v18, 1, v8
	s_addc_u32 s95, s25, s9
	v_and_b32_e32 v18, 24, v18
	s_lshl_b32 s19, s1, 5
	v_readlane_b32 s20, v253, 8
	v_and_b32_e32 v9, 15, v8
	v_lshlrev_b32_e32 v19, 1, v18
	v_lshlrev_b32_e32 v8, 2, v8
	s_and_b32 s22, s19, 0x60
	v_lshl_add_u64 v[10:11], s[70:71], 0, v[0:1]
	v_mov_b32_e32 v181, v1
	v_lshl_or_b32 v229, s6, 6, v9
	v_lshl_or_b32 v9, v9, 6, v19
	s_lshl_b32 s20, s6, 13
	v_and_b32_e32 v8, 32, v8
	s_lshl_b32 s19, s22, 7
	s_add_i32 s48, s40, 0x18000
	v_lshl_add_u64 v[12:13], s[70:71], 0, v[180:181]
	v_mov_b32_e32 v185, v1
	v_bitop3_b32 v230, v9, s20, v8 bitop3:0xde
	v_bitop3_b32 v231, v9, s19, v8 bitop3:0xde
	v_lshl_add_u64 v[8:9], v[10:11], 0, s[50:51]
	s_mov_b32 m0, s48
	s_add_i32 s55, s40, 0x1a000
	v_lshl_add_u64 v[14:15], s[30:31], 0, v[184:185]
	v_mov_b32_e32 v183, v1
	s_waitcnt vmcnt(2)
	s_barrier
	global_load_lds_dwordx4 v[8:9], off
	v_lshl_add_u64 v[8:9], v[12:13], 0, s[50:51]
	s_mov_b32 m0, s55
	s_add_i32 s56, s40, 0x8000
	s_add_i32 s57, s40, 0xa000
	v_lshl_add_u64 v[16:17], s[30:31], 0, v[182:183]
	v_readlane_b32 s21, v253, 9
	global_load_lds_dwordx4 v[8:9], off
	v_lshl_add_u64 v[8:9], v[14:15], 0, s[50:51]
	s_mov_b32 m0, s56
	s_add_u32 s20, s70, 0x40080
	global_load_lds_dwordx4 v[8:9], off
	v_lshl_add_u64 v[8:9], v[16:17], 0, s[50:51]
	s_mov_b32 m0, s57
	s_addc_u32 s21, s71, 0
	s_add_i32 s58, s40, 0x1c000
	global_load_lds_dwordx4 v[8:9], off
	v_lshl_add_u64 v[8:9], s[20:21], 0, v[0:1]
	s_mov_b32 m0, s58
	s_add_i32 s59, s40, 0x1e000
	global_load_lds_dwordx4 v[8:9], off
	v_lshl_add_u64 v[8:9], s[20:21], 0, v[180:181]
	s_mov_b32 m0, s59
	s_cmpk_lt_u32 s0, 0x100
	global_load_lds_dwordx4 v[8:9], off
	v_lshlrev_b32_e32 v8, 14, v2
	v_and_b32_e32 v8, 0xffff8000, v8
	v_lshl_add_u32 v3, v3, 11, v8
	v_and_b32_e32 v2, 1, v2
	v_lshl_or_b32 v2, v2, 6, v3
	v_readlane_b32 s13, v253, 1
	v_readlane_b32 s14, v253, 2
	v_readlane_b32 s15, v253, 3
	v_readlane_b32 s16, v253, 4
	v_readlane_b32 s17, v253, 5
	v_readlane_b32 s18, v253, 6
	s_cselect_b64 s[0:1], -1, 0
	s_and_b64 s[4:5], s[4:5], exec
	v_lshl_add_u32 v186, v4, 1, v2
	v_lshlrev_b32_e32 v2, 14, v6
	v_readlane_b32 s4, v253, 20
	v_and_b32_e32 v2, 0xffff8000, v2
	v_readlane_b32 s26, v253, 14
	v_readlane_b32 s27, v253, 15
	s_waitcnt vmcnt(6)
	v_readlane_b32 s5, v253, 21
	v_lshl_add_u32 v2, v5, 11, v2
	v_and_b32_e32 v3, 1, v6
	s_cselect_b32 s83, s5, s27
	s_cselect_b32 s82, s4, s26
	v_lshl_or_b32 v2, v3, 6, v2
	v_readlane_b32 s4, v253, 51
	s_mov_b32 s54, 0
	v_or_b32_e32 v232, s22, v18
	v_mov_b32_e32 v187, v1
	v_lshl_add_u32 v188, v7, 1, v2
	v_mov_b32_e32 v189, v1
	v_readlane_b32 s61, v253, 50
	s_mov_b32 s60, s4
	s_mov_b32 s79, 0x20000
	s_barrier
	v_readlane_b32 s6, v253, 22
	v_readlane_b32 s7, v253, 23
	v_readlane_b32 s8, v253, 24
	v_readlane_b32 s9, v253, 25
	v_readlane_b32 s10, v253, 26
	v_readlane_b32 s11, v253, 27
	v_readlane_b32 s12, v253, 28
	v_readlane_b32 s13, v253, 29
	v_readlane_b32 s14, v253, 30
	v_readlane_b32 s15, v253, 31
	v_readlane_b32 s16, v253, 32
	v_readlane_b32 s17, v253, 33
	v_readlane_b32 s18, v253, 34
	v_readlane_b32 s19, v253, 35
	v_readlane_b32 s5, v253, 52
	s_branch .LBB0_942
	.p2align	6

;     __device__ __forceinline__ bool next(int i, pg8::Unit& o) const { if (i != 0) return false; o = u; return true; }
; template <class Epi, class Sched, bool ALIGN_EPI = false, bool SP2 = false>
; __device__ __forceinline__ void gemm_phase(PG8_LAS unsigned char* lds, const Gemm g, const Sched& S, const Epi& E) {
;     ...
;         const bool has_next = S.next(ui + 1, nxt);
;         const char* nA = has_next ? (const char*)g.A + (size_t)nxt.pm * tstep : cA; const char* nB = has_next ? (const char*)g.Bt + (size_t)nxt.pn * tstep : cB;
;         for (int t = 0; t < nt; t += 2) {
;             const bool last = (t == nt - 2);
;             const char* a1 = cA + (size_t)(t + 1) * kstep;
;             const char* a2 = last ? nA : cA + (size_t)(t + 2) * kstep; const char* b2 = last ? nB : cB + (size_t)(t + 2) * kstep;
;             const char* a3 = a2 + kstep; const char* b3 = b2 + kstep;
;     ...
; #pragma unroll
;         for (int a = 0; a < 2; ++a)
; #pragma unroll
;             for (int b = 0; b < 2; ++b)
; #pragma unroll
;                 for (int m = 0; m < 4; ++m)
; #pragma unroll
;                     for (int n = 0; n < 2; ++n) acc[a][b][m][n] = (f32x4){0.f, 0.f, 0.f, 0.f};
;         cur = nxt; cA = nA; cB = nB; ++ui;
.LBB0_948:
	s_ashr_i32 s25, s24, 31
	s_lshl_b64 s[26:27], s[24:25], 19
	s_add_u32 s26, s38, s26
	s_addc_u32 s27, s39, s27
	s_and_b64 s[28:29], s[4:5], exec
	s_cselect_b32 s25, s27, s31
	s_cselect_b32 s62, s26, s30
	s_ashr_i32 s85, s84, 31
	s_lshl_b64 s[28:29], s[84:85], 19
	s_add_u32 s28, s3, s28
	s_addc_u32 s29, s37, s29
	s_and_b64 s[34:35], s[4:5], exec
	s_cselect_b32 s23, s29, s71
	s_cselect_b32 s66, s28, s70
	s_add_u32 s69, s70, 0x100
	s_addc_u32 s70, s71, 0
	s_add_u32 s6, s30, 0x40080
	v_mov_b32_e32 v2, 0
	s_addc_u32 s7, s31, 0
	s_mov_b32 s71, -2
	v_mov_b32_e32 v3, v2
	v_mov_b32_e32 v4, v2
	v_mov_b32_e32 v5, v2
	v_mov_b32_e32 v6, v2
	v_mov_b32_e32 v7, v2
	v_mov_b32_e32 v8, v2
	v_mov_b32_e32 v9, v2
	v_mov_b32_e32 v14, v2
	v_mov_b32_e32 v15, v2
	v_mov_b32_e32 v16, v2
	v_mov_b32_e32 v17, v2
	v_mov_b32_e32 v10, v2
	v_mov_b32_e32 v11, v2
	v_mov_b32_e32 v12, v2
	v_mov_b32_e32 v13, v2
	v_mov_b32_e32 v18, v2
	v_mov_b32_e32 v19, v2
	v_mov_b32_e32 v20, v2
	v_mov_b32_e32 v21, v2
	v_mov_b32_e32 v22, v2
	v_mov_b32_e32 v23, v2
	v_mov_b32_e32 v24, v2
	v_mov_b32_e32 v25, v2
	v_mov_b32_e32 v30, v2
	v_mov_b32_e32 v31, v2
	v_mov_b32_e32 v32, v2
	v_mov_b32_e32 v33, v2
	v_mov_b32_e32 v26, v2
	v_mov_b32_e32 v27, v2
	v_mov_b32_e32 v28, v2
	v_mov_b32_e32 v29, v2
	v_mov_b32_e32 v66, v2
	v_mov_b32_e32 v67, v2
	v_mov_b32_e32 v68, v2
	v_mov_b32_e32 v69, v2
	v_mov_b32_e32 v70, v2
	v_mov_b32_e32 v71, v2
	v_mov_b32_e32 v72, v2
	v_mov_b32_e32 v73, v2
	v_mov_b32_e32 v78, v2
	v_mov_b32_e32 v79, v2
	v_mov_b32_e32 v80, v2
	v_mov_b32_e32 v81, v2
	v_mov_b32_e32 v74, v2
	v_mov_b32_e32 v75, v2
	v_mov_b32_e32 v76, v2
	v_mov_b32_e32 v77, v2
	v_mov_b32_e32 v82, v2
	v_mov_b32_e32 v83, v2
	v_mov_b32_e32 v84, v2
	v_mov_b32_e32 v85, v2
	v_mov_b32_e32 v86, v2
	v_mov_b32_e32 v87, v2
	v_mov_b32_e32 v88, v2
	v_mov_b32_e32 v89, v2
	v_mov_b32_e32 v94, v2
	v_mov_b32_e32 v95, v2
	v_mov_b32_e32 v96, v2
	v_mov_b32_e32 v97, v2
	v_mov_b32_e32 v90, v2
	v_mov_b32_e32 v91, v2
	v_mov_b32_e32 v92, v2
	v_mov_b32_e32 v93, v2
	v_mov_b32_e32 v34, v2
	v_mov_b32_e32 v35, v2
	v_mov_b32_e32 v36, v2
	v_mov_b32_e32 v37, v2
	v_mov_b32_e32 v38, v2
	v_mov_b32_e32 v39, v2
	v_mov_b32_e32 v40, v2
	v_mov_b32_e32 v41, v2
	v_mov_b32_e32 v46, v2
	v_mov_b32_e32 v47, v2
	v_mov_b32_e32 v48, v2
	v_mov_b32_e32 v49, v2
	v_mov_b32_e32 v42, v2
	v_mov_b32_e32 v43, v2
	v_mov_b32_e32 v44, v2
	v_mov_b32_e32 v45, v2
	v_mov_b32_e32 v50, v2
	v_mov_b32_e32 v51, v2
	v_mov_b32_e32 v52, v2
	v_mov_b32_e32 v53, v2
	v_mov_b32_e32 v54, v2
	v_mov_b32_e32 v55, v2
	v_mov_b32_e32 v56, v2
	v_mov_b32_e32 v57, v2
	v_mov_b32_e32 v62, v2
	v_mov_b32_e32 v63, v2
	v_mov_b32_e32 v64, v2
	v_mov_b32_e32 v65, v2
	v_mov_b32_e32 v58, v2
	v_mov_b32_e32 v59, v2
	v_mov_b32_e32 v60, v2
	v_mov_b32_e32 v61, v2
	v_mov_b32_e32 v98, v2
	v_mov_b32_e32 v99, v2
	v_mov_b32_e32 v100, v2
	v_mov_b32_e32 v101, v2
	v_mov_b32_e32 v102, v2
	v_mov_b32_e32 v103, v2
	v_mov_b32_e32 v104, v2
	v_mov_b32_e32 v105, v2
	v_mov_b32_e32 v110, v2
	v_mov_b32_e32 v111, v2
	v_mov_b32_e32 v112, v2
	v_mov_b32_e32 v113, v2
	v_mov_b32_e32 v106, v2
	v_mov_b32_e32 v107, v2
	v_mov_b32_e32 v108, v2
	v_mov_b32_e32 v109, v2
	v_mov_b32_e32 v114, v2
	v_mov_b32_e32 v115, v2
	v_mov_b32_e32 v116, v2
	v_mov_b32_e32 v117, v2
	v_mov_b32_e32 v118, v2
	v_mov_b32_e32 v119, v2
	v_mov_b32_e32 v120, v2
	v_mov_b32_e32 v121, v2
	v_mov_b32_e32 v126, v2
	v_mov_b32_e32 v127, v2
	v_mov_b32_e32 v128, v2
	v_mov_b32_e32 v129, v2
	v_mov_b32_e32 v122, v2
	v_mov_b32_e32 v123, v2
	v_mov_b32_e32 v124, v2
	v_mov_b32_e32 v125, v2
	.p2align	6
